# attention main loop: drop redundant max(x,x) canonicalisations and the +0.0 row-sum add
# baseline (speedup 1.0000x reference)
.LBB0_295:
	v_add_u32_e32 v184, s0, v253
	ds_read_b64_tr_b16 v[176:177], v184 offset:24576
	ds_read_b64_tr_b16 v[178:179], v184 offset:25088
	s_waitcnt lgkmcnt(9)
	v_mfma_f32_32x32x16_bf16 v[96:111], v[172:175], v[116:119], v[32:47]
	v_add_f32_e32 v80, v64, v65
	v_add_f32_e32 v80, v66, v80
	v_add_f32_e32 v80, v67, v80
	v_add_f32_e32 v80, v68, v80
	v_add_f32_e32 v80, v69, v80
	v_cvt_pk_bf16_f32 v140, v64, v65
	v_cvt_pk_bf16_f32 v141, v66, v67
	ds_read_b64_tr_b16 v[172:173], v184 offset:28672
	ds_read_b64_tr_b16 v[174:175], v184 offset:29184
	v_add_f32_e32 v64, v70, v80
	s_waitcnt lgkmcnt(10)
	v_mfma_f32_32x32x16_bf16 v[80:95], v[168:171], v[116:119], v[32:47]
	v_add_f32_e32 v64, v71, v64
	v_add_f32_e32 v64, v72, v64
	v_add_f32_e32 v124, v73, v64
	v_cvt_pk_bf16_f32 v142, v68, v69
	v_cvt_pk_bf16_f32 v143, v70, v71
	ds_read_b64_tr_b16 v[64:65], v184 offset:25600
	ds_read_b64_tr_b16 v[66:67], v184 offset:26112
	s_waitcnt lgkmcnt(11)
	v_mfma_f32_32x32x16_bf16 v[96:111], v[164:167], v[112:115], v[96:111]
	v_add_f32_e32 v68, v74, v124
	v_add_f32_e32 v68, v75, v68
	v_add_f32_e32 v68, v76, v68
	v_add_f32_e32 v124, v77, v68
	v_cvt_pk_bf16_f32 v136, v72, v73
	v_cvt_pk_bf16_f32 v137, v74, v75
	ds_read_b64_tr_b16 v[68:69], v184 offset:29696
	ds_read_b64_tr_b16 v[70:71], v184 offset:30208
	s_waitcnt lgkmcnt(12)
	v_mfma_f32_32x32x16_bf16 v[80:95], v[160:163], v[112:115], v[80:95]
	v_add_f32_e32 v72, v78, v124
	v_add_f32_e32 v72, v79, v72
	v_add_f32_e32 v72, v48, v72
	v_add_f32_e32 v124, v49, v72
	v_cvt_pk_bf16_f32 v138, v76, v77
	v_cvt_pk_bf16_f32 v139, v78, v79
	ds_read_b64_tr_b16 v[72:73], v184 offset:26624
	ds_read_b64_tr_b16 v[74:75], v184 offset:27136
	s_waitcnt lgkmcnt(13)
	v_mfma_f32_32x32x16_bf16 v[96:111], v[156:159], v[120:123], v[96:111]
	v_add_f32_e32 v76, v50, v124
	v_add_f32_e32 v76, v51, v76
	v_add_f32_e32 v76, v52, v76
	v_add_f32_e32 v76, v53, v76
	v_cvt_pk_bf16_f32 v128, v48, v49
	v_cvt_pk_bf16_f32 v129, v50, v51
	ds_read_b64_tr_b16 v[48:49], v184 offset:30720
	ds_read_b64_tr_b16 v[50:51], v184 offset:31232
	s_waitcnt lgkmcnt(14)
	v_mfma_f32_32x32x16_bf16 v[80:95], v[152:155], v[120:123], v[80:95]
	v_add_f32_e32 v76, v54, v76
	v_add_f32_e32 v76, v55, v76
	v_add_f32_e32 v76, v56, v76
	v_add_f32_e32 v76, v57, v76
	v_cvt_pk_bf16_f32 v130, v52, v53
	v_cvt_pk_bf16_f32 v131, v54, v55
	ds_read_b64_tr_b16 v[52:53], v184 offset:27648
	ds_read_b64_tr_b16 v[54:55], v184 offset:28160
	s_waitcnt lgkmcnt(14)
	v_mfma_f32_32x32x16_bf16 v[96:111], v[148:151], v[132:135], v[96:111]
	v_add_f32_e32 v76, v58, v76
	v_add_f32_e32 v76, v59, v76
	v_add_f32_e32 v76, v60, v76
	v_add_f32_e32 v76, v61, v76
	v_cvt_pk_bf16_f32 v124, v56, v57
	v_cvt_pk_bf16_f32 v125, v58, v59
	ds_read_b64_tr_b16 v[56:57], v184 offset:31744
	ds_read_b64_tr_b16 v[58:59], v184 offset:32256
	v_mfma_f32_32x32x16_bf16 v[80:95], v[144:147], v[132:135], v[80:95]
	v_add_f32_e32 v76, v62, v76
	v_add_f32_e32 v76, v63, v76
	v_add_f32_e32 v76, 0, v76
	v_cvt_pk_bf16_f32 v126, v60, v61
	v_cvt_pk_bf16_f32 v127, v62, v63
	v_lshl_add_u64 v[60:61], v[182:183], 0, s[8:9]
	s_add_i32 s0, s43, s68
	s_mov_b32 s1, m0
	s_mov_b32 m0, s0
	s_nop 0
	global_load_lds_dwordx4 v[60:61], off
	s_mov_b32 m0, s1
	v_lshl_add_u64 v[60:61], v[180:181], 0, s[8:9]
	s_add_i32 s0, s38, s69
	s_mov_b32 s1, m0
	s_mov_b32 m0, s0
	s_nop 0
	global_load_lds_dwordx4 v[60:61], off
	s_mov_b32 m0, s1
	v_max_f32_e32 v60, v96, v97


	v_max3_f32 v61, v98, v99, v81
	v_max3_f32 v60, v60, v80, v82
	v_max3_f32 v60, v60, v83, v100
	v_max3_f32 v61, v61, v102, v103
	v_max3_f32 v60, v60, v101, v84
	v_max3_f32 v61, v61, v86, v87
	v_max3_f32 v60, v60, v85, v104
	v_max3_f32 v61, v61, v106, v107
	v_max3_f32 v60, v60, v105, v88
	v_max3_f32 v61, v61, v90, v91
	v_max3_f32 v60, v60, v89, v108
	v_max3_f32 v61, v61, v110, v111
	v_max3_f32 v60, v60, v109, v92
	v_max3_f32 v61, v61, v94, v95
	v_max3_f32 v60, v60, v93, v61
	v_mov_b32_e32 v61, v60
	s_nop 1
	v_permlane32_swap_b32_e32 v60, v61


	v_max_f32_e32 v60, v60, v61
	v_cmp_lt_f32_e32 vcc, s84, v60
	s_cmp_lg_u64 vcc, 0
	v_add_f32_e32 v184, v237, v76
	s_cselect_b64 s[36:37], -1, 0
	s_cbranch_vccnz .LBB0_303

.LBB0_298:
	s_add_i32 s0, s38, 0x2000
	s_cmpk_lg_i32 s38, 0x4000
	s_cselect_b32 s71, s0, 0
	v_add_u32_e32 v185, s43, v253
	ds_read_b64_tr_b16 v[148:149], v185 offset:24576
	ds_read_b64_tr_b16 v[150:151], v185 offset:25088
	s_waitcnt lgkmcnt(9)
	v_mfma_f32_32x32x16_bf16 v[64:79], v[60:63], v[116:119], v[32:47]
	v_add_f32_e32 v48, v96, v97
	v_add_f32_e32 v48, v98, v48
	v_add_f32_e32 v48, v99, v48
	v_add_f32_e32 v48, v100, v48
	v_add_f32_e32 v48, v101, v48
	v_cvt_pk_bf16_f32 v140, v96, v97
	v_cvt_pk_bf16_f32 v141, v98, v99
	ds_read_b64_tr_b16 v[144:145], v185 offset:28672
	ds_read_b64_tr_b16 v[146:147], v185 offset:29184
	v_add_f32_e32 v48, v102, v48
	v_add_f32_e32 v48, v103, v48
	v_add_f32_e32 v48, v104, v48
	v_add_f32_e32 v124, v105, v48
	s_waitcnt lgkmcnt(10)
	v_mfma_f32_32x32x16_bf16 v[48:63], v[172:175], v[116:119], v[32:47]
	v_cvt_pk_bf16_f32 v142, v100, v101
	v_cvt_pk_bf16_f32 v143, v102, v103
	ds_read_b64_tr_b16 v[96:97], v185 offset:25600
	ds_read_b64_tr_b16 v[98:99], v185 offset:26112
	s_waitcnt lgkmcnt(11)
	v_mfma_f32_32x32x16_bf16 v[64:79], v[176:179], v[112:115], v[64:79]
	v_add_f32_e32 v100, v106, v124
	v_add_f32_e32 v100, v107, v100
	v_add_f32_e32 v100, v108, v100
	v_add_f32_e32 v124, v109, v100
	v_cvt_pk_bf16_f32 v136, v104, v105
	v_cvt_pk_bf16_f32 v137, v106, v107
	ds_read_b64_tr_b16 v[100:101], v185 offset:29696
	ds_read_b64_tr_b16 v[102:103], v185 offset:30208
	s_waitcnt lgkmcnt(12)
	v_mfma_f32_32x32x16_bf16 v[48:63], v[168:171], v[112:115], v[48:63]
	v_add_f32_e32 v104, v110, v124
	v_add_f32_e32 v104, v111, v104
	v_add_f32_e32 v104, v80, v104
	v_add_f32_e32 v124, v81, v104
	v_cvt_pk_bf16_f32 v138, v108, v109
	v_cvt_pk_bf16_f32 v139, v110, v111
	ds_read_b64_tr_b16 v[104:105], v185 offset:26624
	ds_read_b64_tr_b16 v[106:107], v185 offset:27136
	s_waitcnt lgkmcnt(13)
	v_mfma_f32_32x32x16_bf16 v[64:79], v[164:167], v[120:123], v[64:79]
	v_add_f32_e32 v108, v82, v124
	v_add_f32_e32 v108, v83, v108
	v_add_f32_e32 v108, v84, v108
	v_add_f32_e32 v108, v85, v108
	v_cvt_pk_bf16_f32 v128, v80, v81
	v_cvt_pk_bf16_f32 v129, v82, v83
	ds_read_b64_tr_b16 v[80:81], v185 offset:30720
	ds_read_b64_tr_b16 v[82:83], v185 offset:31232
	s_waitcnt lgkmcnt(14)
	v_mfma_f32_32x32x16_bf16 v[48:63], v[160:163], v[120:123], v[48:63]
	v_add_f32_e32 v108, v86, v108
	v_add_f32_e32 v108, v87, v108
	v_add_f32_e32 v108, v88, v108
	v_add_f32_e32 v108, v89, v108
	v_cvt_pk_bf16_f32 v130, v84, v85
	v_cvt_pk_bf16_f32 v131, v86, v87
	ds_read_b64_tr_b16 v[84:85], v185 offset:27648
	ds_read_b64_tr_b16 v[86:87], v185 offset:28160
	s_waitcnt lgkmcnt(14)
	v_mfma_f32_32x32x16_bf16 v[64:79], v[156:159], v[132:135], v[64:79]
	v_add_f32_e32 v108, v90, v108
	v_add_f32_e32 v108, v91, v108
	v_add_f32_e32 v108, v92, v108
	v_add_f32_e32 v108, v93, v108
	v_cvt_pk_bf16_f32 v124, v88, v89
	v_cvt_pk_bf16_f32 v125, v90, v91
	ds_read_b64_tr_b16 v[88:89], v185 offset:31744
	ds_read_b64_tr_b16 v[90:91], v185 offset:32256
	v_mfma_f32_32x32x16_bf16 v[48:63], v[152:155], v[132:135], v[48:63]
	v_add_f32_e32 v108, v94, v108
	v_add_f32_e32 v108, v95, v108
	v_add_f32_e32 v108, 0, v108
	v_cvt_pk_bf16_f32 v126, v92, v93
	v_cvt_pk_bf16_f32 v127, v94, v95
	v_max_f32_e32 v92, v64, v65


	s_nop 6
	v_max3_f32 v93, v66, v67, v49
	v_max3_f32 v92, v92, v48, v50
	v_max3_f32 v92, v92, v51, v68
	v_max3_f32 v93, v93, v70, v71
	v_max3_f32 v92, v92, v69, v52
	v_max3_f32 v93, v93, v54, v55
	v_max3_f32 v92, v92, v53, v72
	v_max3_f32 v93, v93, v74, v75
	v_max3_f32 v92, v92, v73, v56
	v_max3_f32 v93, v93, v58, v59
	v_max3_f32 v92, v92, v57, v76
	v_max3_f32 v93, v93, v78, v79
	v_max3_f32 v92, v92, v77, v60
	v_max3_f32 v93, v93, v62, v63
	v_max3_f32 v92, v92, v61, v93
	v_mov_b32_e32 v93, v92
	s_nop 1
	v_permlane32_swap_b32_e32 v92, v93


	s_add_i32 s0, s38, s68
	s_mov_b32 s1, m0
	s_mov_b32 m0, s0
	s_nop 0
	global_load_lds_dwordx4 v[182:183], off
	s_mov_b32 m0, s1
	v_max_f32_e32 v92, v92, v93
	s_add_i32 s0, s71, s69
	s_mov_b32 s1, m0
	s_mov_b32 m0, s0
	s_nop 0
	global_load_lds_dwordx4 v[180:181], off
	s_mov_b32 m0, s1
	v_cmp_lt_f32_e32 vcc, s84, v92
	s_cmp_lg_u64 vcc, 0
	v_add_f32_e32 v237, v184, v108
	s_cselect_b64 s[36:37], -1, 0
	s_cbranch_vccnz .LBB0_306
